# plus: k_pe rope loads batched; grid barrier XCD leader publishes generation before its own acquire invalidate
# baseline (speedup 1.0000x reference)
; __device__ __forceinline__ unsigned xb_ld(unsigned* p)              { return __hip_atomic_load(p, __ATOMIC_RELAXED, __HIP_MEMORY_SCOPE_AGENT); }
; __device__ __forceinline__ unsigned xb_add(unsigned* p, unsigned v) { return __hip_atomic_fetch_add(p, v, __ATOMIC_RELAXED, __HIP_MEMORY_SCOPE_AGENT); }
; #define XB_SPIN(cond, bar) do { unsigned _sp = 0; while (cond) { __builtin_amdgcn_s_sleep(1); \
;     if ((++_sp & 255u) == 0u) { if (xb_ld(&(bar)[XB_TMO])) break; if (_sp > XB_SPIN_CAP) { atomicAdd(&(bar)[XB_TMO], 1u); break; } } } } while (0)
; __device__ __forceinline__ void xcd_barrier(const XcdBarrier& b) {
;     ...
;             __builtin_amdgcn_fence(__ATOMIC_RELEASE, "agent");
;             asm volatile("s_waitcnt vmcnt(0)" ::: "memory");
;             const unsigned og = xb_add(&bar[XB_TOP], 1u);
;             const unsigned tg = og / nx;
;             if (og + 1u == (tg + 1u) * nx) xb_add(&bar[XB_TOPGEN], 1u);
;             else XB_SPIN(xb_ld(&bar[XB_TOPGEN]) == tg, bar);
;             __builtin_amdgcn_fence(__ATOMIC_ACQUIRE, "agent");
;             xb_add(&bar[XB_XGEN(b.x)], 1u);
;             asm volatile("s_waitcnt vmcnt(0)" ::: "memory");
.LBB0_617:
	s_or_b64 exec, exec, s[6:7]
	s_add_i32 s6, s24, 0x900
	s_mov_b32 s7, 0
	s_lshl_b64 s[6:7], s[6:7], 2
	s_add_u32 s4, s4, s6
	s_addc_u32 s5, s5, s7
	v_mov_b32_e32 v1, 0
	v_mov_b32_e32 v2, 1
	s_waitcnt vmcnt(0)
	global_atomic_add v1, v2, s[4:5]
	buffer_inv sc1
	s_waitcnt vmcnt(0)

; __device__ __forceinline__ unsigned xb_ld(unsigned* p)              { return __hip_atomic_load(p, __ATOMIC_RELAXED, __HIP_MEMORY_SCOPE_AGENT); }
; __device__ __forceinline__ unsigned xb_add(unsigned* p, unsigned v) { return __hip_atomic_fetch_add(p, v, __ATOMIC_RELAXED, __HIP_MEMORY_SCOPE_AGENT); }
; #define XB_SPIN(cond, bar) do { unsigned _sp = 0; while (cond) { __builtin_amdgcn_s_sleep(1); \
;     if ((++_sp & 255u) == 0u) { if (xb_ld(&(bar)[XB_TMO])) break; if (_sp > XB_SPIN_CAP) { atomicAdd(&(bar)[XB_TMO], 1u); break; } } } } while (0)
; __device__ __forceinline__ void xcd_barrier(const XcdBarrier& b) {
;     ...
;             __builtin_amdgcn_fence(__ATOMIC_RELEASE, "agent");
;             asm volatile("s_waitcnt vmcnt(0)" ::: "memory");
;             const unsigned og = xb_add(&bar[XB_TOP], 1u);
;             const unsigned tg = og / nx;
;             if (og + 1u == (tg + 1u) * nx) xb_add(&bar[XB_TOPGEN], 1u);
;             else XB_SPIN(xb_ld(&bar[XB_TOPGEN]) == tg, bar);
;             __builtin_amdgcn_fence(__ATOMIC_ACQUIRE, "agent");
;             xb_add(&bar[XB_XGEN(b.x)], 1u);
;             asm volatile("s_waitcnt vmcnt(0)" ::: "memory");
.LBB0_620:
	s_or_b64 exec, exec, s[4:5]
	s_add_i32 s92, s22, 0x900
	s_lshl_b64 s[4:5], s[92:93], 2
	s_add_u32 s2, s2, s4
	s_addc_u32 s3, s3, s5
	s_waitcnt vmcnt(0)
	global_atomic_add v35, v228, s[2:3]
	buffer_inv sc1
	s_waitcnt vmcnt(0)

; __device__ __forceinline__ unsigned xb_ld(unsigned* p)              { return __hip_atomic_load(p, __ATOMIC_RELAXED, __HIP_MEMORY_SCOPE_AGENT); }
; __device__ __forceinline__ unsigned xb_add(unsigned* p, unsigned v) { return __hip_atomic_fetch_add(p, v, __ATOMIC_RELAXED, __HIP_MEMORY_SCOPE_AGENT); }
; #define XB_SPIN(cond, bar) do { unsigned _sp = 0; while (cond) { __builtin_amdgcn_s_sleep(1); \
;     if ((++_sp & 255u) == 0u) { if (xb_ld(&(bar)[XB_TMO])) break; if (_sp > XB_SPIN_CAP) { atomicAdd(&(bar)[XB_TMO], 1u); break; } } } } while (0)
; __device__ __forceinline__ void xcd_barrier(const XcdBarrier& b) {
;     ...
;             __builtin_amdgcn_fence(__ATOMIC_RELEASE, "agent");
;             asm volatile("s_waitcnt vmcnt(0)" ::: "memory");
;             const unsigned og = xb_add(&bar[XB_TOP], 1u);
;             const unsigned tg = og / nx;
;             if (og + 1u == (tg + 1u) * nx) xb_add(&bar[XB_TOPGEN], 1u);
;             else XB_SPIN(xb_ld(&bar[XB_TOPGEN]) == tg, bar);
;             __builtin_amdgcn_fence(__ATOMIC_ACQUIRE, "agent");
;             xb_add(&bar[XB_XGEN(b.x)], 1u);
;             asm volatile("s_waitcnt vmcnt(0)" ::: "memory");
.LBB0_754:
	s_or_b64 exec, exec, s[4:5]
	s_add_i32 s92, s23, 0x900
	s_lshl_b64 s[4:5], s[92:93], 2
	s_add_u32 s2, s2, s4
	s_addc_u32 s3, s3, s5
	s_waitcnt vmcnt(0)
	global_atomic_add v35, v228, s[2:3]
	buffer_inv sc1
	s_waitcnt vmcnt(0)

; __device__ __forceinline__ float bf2f(bf16_t b) { return __uint_as_float(((unsigned)b) << 16); }
; __device__ __forceinline__ bf16_t f2bf(float f) { return (bf16_t)(cvt_pk_bf16(f, 0.f) & 0xffffu); }
; __global__ void __launch_bounds__(512, 2) hybrid_fwd(Args args) {
;     ...
;                     if (pn == 0) { const float* rope = WSP(const float, WS_ROPEM); bf16_t* Kb = WSP(bf16_t, WS_K);
; #pragma unroll
;                         for (int i8 = 0; i8 < 8; ++i8) { const int i = F.tid + i8 * 512; const int lr = i >> 4, j = i & 15, t = pm * 256 + lr, b = t >> 11, s = t & 2047;
;                             const float x1 = bf2f(H[(size_t)t * HP + C_KR + j]), x2 = bf2f(H[(size_t)t * HP + C_KR + 16 + j]), c = rope[t * 32 + j], sn = rope[t * 32 + 16 + j];
;                             const bf16_t o1 = f2bf(x1 * c - x2 * sn), o2 = f2bf(x2 * c + x1 * sn);
; #pragma unroll
;                             for (int hd = 0; hd < 4; ++hd) { bf16_t* kp = Kb + ((size_t)((b * 4 + hd) * SEQ + s)) * 96; kp[64 + j] = o1; kp[80 + j] = o2; } } } }
.LBB0_843:
.LBB0_844:
	s_waitcnt vmcnt(0)
	s_cmp_lg_u32 s26, 0
	s_barrier
	s_cbranch_scc1 .LBB0_846
	v_and_b32_e32 v6, 15, v140
	v_ashrrev_i32_e32 v4, 4, v140
	v_lshlrev_b32_e32 v34, 1, v6
	v_add_u32_e32 v16, s23, v4
	v_mov_b64_e32 v[4:5], s[12:13]
	s_movk_i32 s16, 0x1600
	v_lshl_add_u64 v[2:3], s[4:5], 0, v[34:35]
	s_add_u32 s0, s10, 0x1ce00000
	s_addc_u32 s1, s11, 0
	s_movk_i32 s17, 0xe000
	v_add_u32_e32 v17, 32, v16
	v_add_u32_e32 v18, 64, v16
	v_add_u32_e32 v19, 0x60, v16
	v_add_u32_e32 v20, 0x80, v16
	v_add_u32_e32 v21, 0xa0, v16
	v_add_u32_e32 v22, 0xc0, v16
	v_add_u32_e32 v23, 0xe0, v16
	v_mad_i64_i32 v[8:9], s[4:5], v16, s16, v[4:5]
	v_lshl_or_b32 v10, v16, 5, v6
	v_lshl_add_u64 v[8:9], v[8:9], 0, v[34:35]
	v_ashrrev_i32_e32 v11, 31, v10
	global_load_ushort v44, v[8:9], off offset:1280
	global_load_ushort v52, v[8:9], off offset:1312
	v_lshl_add_u64 v[10:11], v[10:11], 2, s[0:1]
	global_load_dword v60, v[10:11], off
	global_load_dword v68, v[10:11], off offset:64
	v_mad_i64_i32 v[8:9], s[4:5], v17, s16, v[4:5]
	v_lshl_or_b32 v10, v17, 5, v6
	v_lshl_add_u64 v[8:9], v[8:9], 0, v[34:35]
	v_ashrrev_i32_e32 v11, 31, v10
	global_load_ushort v45, v[8:9], off offset:1280
	global_load_ushort v53, v[8:9], off offset:1312
	v_lshl_add_u64 v[10:11], v[10:11], 2, s[0:1]
	global_load_dword v61, v[10:11], off
	global_load_dword v69, v[10:11], off offset:64
	v_mad_i64_i32 v[8:9], s[4:5], v18, s16, v[4:5]
	v_lshl_or_b32 v10, v18, 5, v6
	v_lshl_add_u64 v[8:9], v[8:9], 0, v[34:35]
	v_ashrrev_i32_e32 v11, 31, v10
	global_load_ushort v46, v[8:9], off offset:1280
	global_load_ushort v54, v[8:9], off offset:1312
	v_lshl_add_u64 v[10:11], v[10:11], 2, s[0:1]
	global_load_dword v62, v[10:11], off
	global_load_dword v70, v[10:11], off offset:64
	v_mad_i64_i32 v[8:9], s[4:5], v19, s16, v[4:5]
	v_lshl_or_b32 v10, v19, 5, v6
	v_lshl_add_u64 v[8:9], v[8:9], 0, v[34:35]
	v_ashrrev_i32_e32 v11, 31, v10
	global_load_ushort v47, v[8:9], off offset:1280
	global_load_ushort v55, v[8:9], off offset:1312
	v_lshl_add_u64 v[10:11], v[10:11], 2, s[0:1]
	global_load_dword v63, v[10:11], off
	global_load_dword v71, v[10:11], off offset:64
	v_mad_i64_i32 v[8:9], s[4:5], v20, s16, v[4:5]
	v_lshl_or_b32 v10, v20, 5, v6
	v_lshl_add_u64 v[8:9], v[8:9], 0, v[34:35]
	v_ashrrev_i32_e32 v11, 31, v10
	global_load_ushort v48, v[8:9], off offset:1280
	global_load_ushort v56, v[8:9], off offset:1312
	v_lshl_add_u64 v[10:11], v[10:11], 2, s[0:1]
	global_load_dword v64, v[10:11], off
	global_load_dword v72, v[10:11], off offset:64
	v_mad_i64_i32 v[8:9], s[4:5], v21, s16, v[4:5]
	v_lshl_or_b32 v10, v21, 5, v6
	v_lshl_add_u64 v[8:9], v[8:9], 0, v[34:35]
	v_ashrrev_i32_e32 v11, 31, v10
	global_load_ushort v49, v[8:9], off offset:1280
	global_load_ushort v57, v[8:9], off offset:1312
	v_lshl_add_u64 v[10:11], v[10:11], 2, s[0:1]
	global_load_dword v65, v[10:11], off
	global_load_dword v73, v[10:11], off offset:64
	v_mad_i64_i32 v[8:9], s[4:5], v22, s16, v[4:5]
	v_lshl_or_b32 v10, v22, 5, v6
	v_lshl_add_u64 v[8:9], v[8:9], 0, v[34:35]
	v_ashrrev_i32_e32 v11, 31, v10
	global_load_ushort v50, v[8:9], off offset:1280
	global_load_ushort v58, v[8:9], off offset:1312
	v_lshl_add_u64 v[10:11], v[10:11], 2, s[0:1]
	global_load_dword v66, v[10:11], off
	global_load_dword v74, v[10:11], off offset:64
	v_mad_i64_i32 v[8:9], s[4:5], v23, s16, v[4:5]
	v_lshl_or_b32 v10, v23, 5, v6
	v_lshl_add_u64 v[8:9], v[8:9], 0, v[34:35]
	v_ashrrev_i32_e32 v11, 31, v10
	global_load_ushort v51, v[8:9], off offset:1280
	global_load_ushort v59, v[8:9], off offset:1312
	v_lshl_add_u64 v[10:11], v[10:11], 2, s[0:1]
	global_load_dword v67, v[10:11], off
	global_load_dword v75, v[10:11], off offset:64
	s_waitcnt vmcnt(0)
	v_lshlrev_b32_e32 v11, 16, v44
	v_lshlrev_b32_e32 v12, 16, v52
	v_and_b32_e32 v10, 0x7ff, v16
	v_lshlrev_b32_e32 v7, 2, v16
	v_mul_f32_e32 v9, v68, v12
	v_and_or_b32 v7, v7, s17, v10
	v_fma_f32 v9, v60, v11, -v9
	v_mul_f32_e32 v13, v60, v12
	v_cvt_pk_bf16_f32 v76, v9, v35
	v_fmac_f32_e32 v13, v68, v11
	v_mad_i64_i32 v[8:9], s[4:5], v7, s95, v[2:3]
	v_cvt_pk_bf16_f32 v84, v13, v35
	global_store_short v[8:9], v76, off offset:128
	global_store_short v[8:9], v84, off offset:160
	v_or_b32_e32 v8, 0x800, v7
	v_mad_i64_i32 v[8:9], s[4:5], v8, s95, v[2:3]
	global_store_short v[8:9], v76, off offset:128
	global_store_short v[8:9], v84, off offset:160
	v_or_b32_e32 v8, 0x1000, v7
	v_mad_i64_i32 v[8:9], s[4:5], v8, s95, v[2:3]
	global_store_short v[8:9], v76, off offset:128
	global_store_short v[8:9], v84, off offset:160
	v_or_b32_e32 v8, 0x1800, v7
	v_mad_i64_i32 v[8:9], s[4:5], v8, s95, v[2:3]
	global_store_short v[8:9], v76, off offset:128
	global_store_short v[8:9], v84, off offset:160
	v_lshlrev_b32_e32 v11, 16, v45
	v_lshlrev_b32_e32 v12, 16, v53
	v_and_b32_e32 v10, 0x7ff, v17
	v_lshlrev_b32_e32 v7, 2, v17
	v_mul_f32_e32 v9, v69, v12
	v_and_or_b32 v7, v7, s17, v10
	v_fma_f32 v9, v61, v11, -v9
	v_mul_f32_e32 v13, v61, v12
	v_cvt_pk_bf16_f32 v77, v9, v35
	v_fmac_f32_e32 v13, v69, v11
	v_mad_i64_i32 v[8:9], s[4:5], v7, s95, v[2:3]
	v_cvt_pk_bf16_f32 v85, v13, v35
	global_store_short v[8:9], v77, off offset:128
	global_store_short v[8:9], v85, off offset:160
	v_or_b32_e32 v8, 0x800, v7
	v_mad_i64_i32 v[8:9], s[4:5], v8, s95, v[2:3]
	global_store_short v[8:9], v77, off offset:128
	global_store_short v[8:9], v85, off offset:160
	v_or_b32_e32 v8, 0x1000, v7
	v_mad_i64_i32 v[8:9], s[4:5], v8, s95, v[2:3]
	global_store_short v[8:9], v77, off offset:128
	global_store_short v[8:9], v85, off offset:160
	v_or_b32_e32 v8, 0x1800, v7
	v_mad_i64_i32 v[8:9], s[4:5], v8, s95, v[2:3]
	global_store_short v[8:9], v77, off offset:128
; __device__ __forceinline__ float bf2f(bf16_t b) { return __uint_as_float(((unsigned)b) << 16); }
; __device__ __forceinline__ bf16_t f2bf(float f) { return (bf16_t)(cvt_pk_bf16(f, 0.f) & 0xffffu); }
; __global__ void __launch_bounds__(512, 2) hybrid_fwd(Args args) {
;     ...
;                         for (int i8 = 0; i8 < 8; ++i8) { const int i = F.tid + i8 * 512; const int lr = i >> 4, j = i & 15, t = pm * 256 + lr, b = t >> 11, s = t & 2047;
;                             const float x1 = bf2f(H[(size_t)t * HP + C_KR + j]), x2 = bf2f(H[(size_t)t * HP + C_KR + 16 + j]), c = rope[t * 32 + j], sn = rope[t * 32 + 16 + j];
;                             const bf16_t o1 = f2bf(x1 * c - x2 * sn), o2 = f2bf(x2 * c + x1 * sn);
; #pragma unroll
;                             for (int hd = 0; hd < 4; ++hd) { bf16_t* kp = Kb + ((size_t)((b * 4 + hd) * SEQ + s)) * 96; kp[64 + j] = o1; kp[80 + j] = o2; } } } }
	global_store_short v[8:9], v85, off offset:160
	v_lshlrev_b32_e32 v11, 16, v46
	v_lshlrev_b32_e32 v12, 16, v54
	v_and_b32_e32 v10, 0x7ff, v18
	v_lshlrev_b32_e32 v7, 2, v18
	v_mul_f32_e32 v9, v70, v12
	v_and_or_b32 v7, v7, s17, v10
	v_fma_f32 v9, v62, v11, -v9
	v_mul_f32_e32 v13, v62, v12
	v_cvt_pk_bf16_f32 v78, v9, v35
	v_fmac_f32_e32 v13, v70, v11
	v_mad_i64_i32 v[8:9], s[4:5], v7, s95, v[2:3]
	v_cvt_pk_bf16_f32 v86, v13, v35
	global_store_short v[8:9], v78, off offset:128
	global_store_short v[8:9], v86, off offset:160
	v_or_b32_e32 v8, 0x800, v7
	v_mad_i64_i32 v[8:9], s[4:5], v8, s95, v[2:3]
	global_store_short v[8:9], v78, off offset:128
	global_store_short v[8:9], v86, off offset:160
	v_or_b32_e32 v8, 0x1000, v7
	v_mad_i64_i32 v[8:9], s[4:5], v8, s95, v[2:3]
	global_store_short v[8:9], v78, off offset:128
	global_store_short v[8:9], v86, off offset:160
	v_or_b32_e32 v8, 0x1800, v7
	v_mad_i64_i32 v[8:9], s[4:5], v8, s95, v[2:3]
	global_store_short v[8:9], v78, off offset:128
	global_store_short v[8:9], v86, off offset:160
	v_lshlrev_b32_e32 v11, 16, v47
	v_lshlrev_b32_e32 v12, 16, v55
	v_and_b32_e32 v10, 0x7ff, v19
	v_lshlrev_b32_e32 v7, 2, v19
	v_mul_f32_e32 v9, v71, v12
	v_and_or_b32 v7, v7, s17, v10
	v_fma_f32 v9, v63, v11, -v9
	v_mul_f32_e32 v13, v63, v12
	v_cvt_pk_bf16_f32 v79, v9, v35
	v_fmac_f32_e32 v13, v71, v11
	v_mad_i64_i32 v[8:9], s[4:5], v7, s95, v[2:3]
	v_cvt_pk_bf16_f32 v87, v13, v35
	global_store_short v[8:9], v79, off offset:128
	global_store_short v[8:9], v87, off offset:160
	v_or_b32_e32 v8, 0x800, v7
	v_mad_i64_i32 v[8:9], s[4:5], v8, s95, v[2:3]
	global_store_short v[8:9], v79, off offset:128
	global_store_short v[8:9], v87, off offset:160
	v_or_b32_e32 v8, 0x1000, v7
	v_mad_i64_i32 v[8:9], s[4:5], v8, s95, v[2:3]
	global_store_short v[8:9], v79, off offset:128
	global_store_short v[8:9], v87, off offset:160
	v_or_b32_e32 v8, 0x1800, v7
	v_mad_i64_i32 v[8:9], s[4:5], v8, s95, v[2:3]
	global_store_short v[8:9], v79, off offset:128
	global_store_short v[8:9], v87, off offset:160
	v_lshlrev_b32_e32 v11, 16, v48
	v_lshlrev_b32_e32 v12, 16, v56
	v_and_b32_e32 v10, 0x7ff, v20
	v_lshlrev_b32_e32 v7, 2, v20
	v_mul_f32_e32 v9, v72, v12
	v_and_or_b32 v7, v7, s17, v10
	v_fma_f32 v9, v64, v11, -v9
	v_mul_f32_e32 v13, v64, v12
	v_cvt_pk_bf16_f32 v80, v9, v35
	v_fmac_f32_e32 v13, v72, v11
	v_mad_i64_i32 v[8:9], s[4:5], v7, s95, v[2:3]
	v_cvt_pk_bf16_f32 v88, v13, v35
	global_store_short v[8:9], v80, off offset:128
	global_store_short v[8:9], v88, off offset:160
	v_or_b32_e32 v8, 0x800, v7
	v_mad_i64_i32 v[8:9], s[4:5], v8, s95, v[2:3]
	global_store_short v[8:9], v80, off offset:128
	global_store_short v[8:9], v88, off offset:160
	v_or_b32_e32 v8, 0x1000, v7
	v_mad_i64_i32 v[8:9], s[4:5], v8, s95, v[2:3]
	global_store_short v[8:9], v80, off offset:128
	global_store_short v[8:9], v88, off offset:160
	v_or_b32_e32 v8, 0x1800, v7
	v_mad_i64_i32 v[8:9], s[4:5], v8, s95, v[2:3]
	global_store_short v[8:9], v80, off offset:128
	global_store_short v[8:9], v88, off offset:160
	v_lshlrev_b32_e32 v11, 16, v49
	v_lshlrev_b32_e32 v12, 16, v57
	v_and_b32_e32 v10, 0x7ff, v21
	v_lshlrev_b32_e32 v7, 2, v21
	v_mul_f32_e32 v9, v73, v12
	v_and_or_b32 v7, v7, s17, v10
	v_fma_f32 v9, v65, v11, -v9
	v_mul_f32_e32 v13, v65, v12
	v_cvt_pk_bf16_f32 v81, v9, v35
	v_fmac_f32_e32 v13, v73, v11
	v_mad_i64_i32 v[8:9], s[4:5], v7, s95, v[2:3]
	v_cvt_pk_bf16_f32 v89, v13, v35
	global_store_short v[8:9], v81, off offset:128
	global_store_short v[8:9], v89, off offset:160
	v_or_b32_e32 v8, 0x800, v7
	v_mad_i64_i32 v[8:9], s[4:5], v8, s95, v[2:3]
	global_store_short v[8:9], v81, off offset:128
	global_store_short v[8:9], v89, off offset:160
	v_or_b32_e32 v8, 0x1000, v7
	v_mad_i64_i32 v[8:9], s[4:5], v8, s95, v[2:3]
	global_store_short v[8:9], v81, off offset:128
	global_store_short v[8:9], v89, off offset:160
	v_or_b32_e32 v8, 0x1800, v7
	v_mad_i64_i32 v[8:9], s[4:5], v8, s95, v[2:3]
	global_store_short v[8:9], v81, off offset:128
	global_store_short v[8:9], v89, off offset:160
	v_lshlrev_b32_e32 v11, 16, v50
	v_lshlrev_b32_e32 v12, 16, v58
	v_and_b32_e32 v10, 0x7ff, v22
	v_lshlrev_b32_e32 v7, 2, v22
	v_mul_f32_e32 v9, v74, v12
	v_and_or_b32 v7, v7, s17, v10
	v_fma_f32 v9, v66, v11, -v9
	v_mul_f32_e32 v13, v66, v12
	v_cvt_pk_bf16_f32 v82, v9, v35
	v_fmac_f32_e32 v13, v74, v11
	v_mad_i64_i32 v[8:9], s[4:5], v7, s95, v[2:3]
	v_cvt_pk_bf16_f32 v90, v13, v35
	global_store_short v[8:9], v82, off offset:128
	global_store_short v[8:9], v90, off offset:160
	v_or_b32_e32 v8, 0x800, v7
	v_mad_i64_i32 v[8:9], s[4:5], v8, s95, v[2:3]
	global_store_short v[8:9], v82, off offset:128
	global_store_short v[8:9], v90, off offset:160
	v_or_b32_e32 v8, 0x1000, v7
	v_mad_i64_i32 v[8:9], s[4:5], v8, s95, v[2:3]
	global_store_short v[8:9], v82, off offset:128
	global_store_short v[8:9], v90, off offset:160
	v_or_b32_e32 v8, 0x1800, v7
	v_mad_i64_i32 v[8:9], s[4:5], v8, s95, v[2:3]
	global_store_short v[8:9], v82, off offset:128
	global_store_short v[8:9], v90, off offset:160
	v_lshlrev_b32_e32 v11, 16, v51
	v_lshlrev_b32_e32 v12, 16, v59
	v_and_b32_e32 v10, 0x7ff, v23
	v_lshlrev_b32_e32 v7, 2, v23
	v_mul_f32_e32 v9, v75, v12
	v_and_or_b32 v7, v7, s17, v10
	v_fma_f32 v9, v67, v11, -v9
	v_mul_f32_e32 v13, v67, v12
	v_cvt_pk_bf16_f32 v83, v9, v35
	v_fmac_f32_e32 v13, v75, v11
	v_mad_i64_i32 v[8:9], s[4:5], v7, s95, v[2:3]
	v_cvt_pk_bf16_f32 v91, v13, v35
	global_store_short v[8:9], v83, off offset:128
	global_store_short v[8:9], v91, off offset:160
	v_or_b32_e32 v8, 0x800, v7
	v_mad_i64_i32 v[8:9], s[4:5], v8, s95, v[2:3]
	global_store_short v[8:9], v83, off offset:128
	global_store_short v[8:9], v91, off offset:160
	v_or_b32_e32 v8, 0x1000, v7
	v_mad_i64_i32 v[8:9], s[4:5], v8, s95, v[2:3]
	global_store_short v[8:9], v83, off offset:128
	global_store_short v[8:9], v91, off offset:160
	v_or_b32_e32 v8, 0x1800, v7
	v_mad_i64_i32 v[8:9], s[4:5], v8, s95, v[2:3]
	global_store_short v[8:9], v83, off offset:128
	global_store_short v[8:9], v91, off offset:160

; __device__ __forceinline__ unsigned xb_ld(unsigned* p)              { return __hip_atomic_load(p, __ATOMIC_RELAXED, __HIP_MEMORY_SCOPE_AGENT); }
; __device__ __forceinline__ unsigned xb_add(unsigned* p, unsigned v) { return __hip_atomic_fetch_add(p, v, __ATOMIC_RELAXED, __HIP_MEMORY_SCOPE_AGENT); }
; #define XB_SPIN(cond, bar) do { unsigned _sp = 0; while (cond) { __builtin_amdgcn_s_sleep(1); \
;     if ((++_sp & 255u) == 0u) { if (xb_ld(&(bar)[XB_TMO])) break; if (_sp > XB_SPIN_CAP) { atomicAdd(&(bar)[XB_TMO], 1u); break; } } } } while (0)
; __device__ __forceinline__ void xcd_barrier(const XcdBarrier& b) {
;     ...
;             __builtin_amdgcn_fence(__ATOMIC_RELEASE, "agent");
;             asm volatile("s_waitcnt vmcnt(0)" ::: "memory");
;             const unsigned og = xb_add(&bar[XB_TOP], 1u);
;             const unsigned tg = og / nx;
;             if (og + 1u == (tg + 1u) * nx) xb_add(&bar[XB_TOPGEN], 1u);
;             else XB_SPIN(xb_ld(&bar[XB_TOPGEN]) == tg, bar);
;             __builtin_amdgcn_fence(__ATOMIC_ACQUIRE, "agent");
;             xb_add(&bar[XB_XGEN(b.x)], 1u);
;             asm volatile("s_waitcnt vmcnt(0)" ::: "memory");
.LBB0_1021:
	s_or_b64 exec, exec, s[6:7]
	s_add_i32 s92, s25, 0x900
	s_lshl_b64 s[6:7], s[92:93], 2
	s_add_u32 s4, s4, s6
	s_addc_u32 s5, s5, s7
	s_waitcnt vmcnt(0)
	global_atomic_add v35, v228, s[4:5]
	buffer_inv sc1
	s_waitcnt vmcnt(0)

; __device__ __forceinline__ unsigned xb_ld(unsigned* p)              { return __hip_atomic_load(p, __ATOMIC_RELAXED, __HIP_MEMORY_SCOPE_AGENT); }
; __device__ __forceinline__ unsigned xb_add(unsigned* p, unsigned v) { return __hip_atomic_fetch_add(p, v, __ATOMIC_RELAXED, __HIP_MEMORY_SCOPE_AGENT); }
; #define XB_SPIN(cond, bar) do { unsigned _sp = 0; while (cond) { __builtin_amdgcn_s_sleep(1); \
;     if ((++_sp & 255u) == 0u) { if (xb_ld(&(bar)[XB_TMO])) break; if (_sp > XB_SPIN_CAP) { atomicAdd(&(bar)[XB_TMO], 1u); break; } } } } while (0)
; __device__ __forceinline__ void xcd_barrier(const XcdBarrier& b) {
;     ...
;             __builtin_amdgcn_fence(__ATOMIC_RELEASE, "agent");
;             asm volatile("s_waitcnt vmcnt(0)" ::: "memory");
;             const unsigned og = xb_add(&bar[XB_TOP], 1u);
;             const unsigned tg = og / nx;
;             if (og + 1u == (tg + 1u) * nx) xb_add(&bar[XB_TOPGEN], 1u);
;             else XB_SPIN(xb_ld(&bar[XB_TOPGEN]) == tg, bar);
;             __builtin_amdgcn_fence(__ATOMIC_ACQUIRE, "agent");
;             xb_add(&bar[XB_XGEN(b.x)], 1u);
;             asm volatile("s_waitcnt vmcnt(0)" ::: "memory");
.LBB0_1599:
	s_or_b64 exec, exec, s[6:7]
	s_add_i32 s92, s24, 0x900
	s_lshl_b64 s[6:7], s[92:93], 2
	s_add_u32 s2, s2, s6
	s_addc_u32 s3, s3, s7
	s_waitcnt vmcnt(0)
	global_atomic_add v35, v228, s[2:3]
	buffer_inv sc1
	s_waitcnt vmcnt(0)
